# MLA work queue: q-blocks 56..63 (was 58..63) split into 128-query half items
# baseline (speedup 1.0000x reference)
.LBB0_1382:
	s_or_b64 exec, exec, s[16:17]
	s_add_i32 s16, 0, 0x14000
	v_mov_b32_e32 v0, s16
	s_waitcnt lgkmcnt(0)
	s_barrier
	ds_read_b32 v0, v0
	s_movk_i32 s16, 0x1af
	s_waitcnt lgkmcnt(0)
	s_barrier
	v_cmp_lt_i32_e32 vcc, s16, v0
	v_readfirstlane_b32 s18, v0
	s_mov_b64 s[16:17], -1
	s_cbranch_vccnz .LBB0_1377
	s_cmp_lt_u32 s18, 0x60
	s_cbranch_scc1 .Lmla_half_item
	s_sub_i32 s18, s18, 0x60
	s_mul_hi_u32 s16, s18, 0x2aaaaaab
	s_sub_i32 s20, 55, s16
	s_mul_i32 s16, s16, 6
	s_sub_i32 s16, s18, s16
	s_mov_b32 s31, 4
	s_mov_b32 s30, s14
	v_lshl_add_u32 v196, s20, 8, v231
	s_branch .Lmla_item_ready
